# P9 halo fix-up rewritten by hand: loads of four work items in flight together, scalar row selection (on top of v54)
# baseline (speedup 1.0000x reference)
; __global__ void __launch_bounds__(512) fwd_mega(Args a) {
;     ...
;     if (IN(9)) {
;         constexpr int NF4 = DFF / 4;
;         for (int i = bx * 512 + tid; i < 1024 * NF4; i += G * 512) { const int f = (i % NF4) * 4, rj = i / NF4, jb = rj >> 1, ii = rj & 1; const bool first = (jb & 255) == 0;
;             const f32x4 z = {0.f, 0.f, 0.f, 0.f};
;             const f32x4 a0 = *(const f32x4*)(AH + ((size_t)jb * 4 + 2 + ii) * DFF + f);
;             const f32x4 pm1 = first ? z : *(const f32x4*)(AH + ((size_t)(jb - 1) * 4 + 1) * DFF + f);
;             const f32x4 pm2 = first ? z : *(const f32x4*)(AH + ((size_t)(jb - 1) * 4 + 0) * DFF + f);
;             const f32x4 a1 = ii ? *(const f32x4*)(AH + ((size_t)jb * 4 + 2) * DFF + f) : pm1;
;             const f32x4 a2 = ii ? pm1 : pm2;
;             const f32x4 bv = *(const f32x4*)(BH + ((size_t)jb * 2 + ii) * DFF + f);
;             const f32x4 c = *(const f32x4*)(a.conv_b + f) + *(const f32x4*)(a.conv_w + f) * a2 + *(const f32x4*)(a.conv_w + DFF + f) * a1 + *(const f32x4*)(a.conv_w + 2 * DFF + f) * a0;
.LBB0_943:
	s_cmp_lt_i32 s54, 10
	s_cselect_b64 s[4:5], -1, 0
	s_and_b64 s[4:5], s[4:5], s[0:1]
	s_andn2_b64 vcc, exec, s[4:5]
	s_cbranch_vccnz .LBB0_954
	s_mov_b64 s[6:7], exec
	s_add_u32 s8, s24, 0x5800
	s_addc_u32 s9, s25, 0
	s_add_u32 s0, s24, 0xb000
	s_addc_u32 s1, s25, 0
	v_lshlrev_b32_e32 v2, 4, v206
	v_lshlrev_b32_e32 v3, 3, v206
	v_readfirstlane_b32 s2, v162
	s_nop 3
	s_and_b32 s2, s2, 0x3c0
	s_lshl_b32 s36, s60, 9
	s_add_u32 s2, s2, s36
	s_lshl_b32 s16, s3, 9
	s_mov_b32 s28, s2
	s_cmp_lt_u32 s2, 1441792
	s_cbranch_scc0 .Lp9_done
.Lp9_batch:
	s_mul_i32 s36, s16, 0
	s_add_u32 s17, s2, s36
	s_cmp_lt_u32 s17, 1441792
	s_cselect_b32 s17, s17, s28
	s_lshr_b32 s36, s17, 7
	s_mul_hi_u32 s22, s36, 0xba2e8ba3
	s_lshr_b32 s22, s22, 3
	s_mul_i32 s36, s22, 1408
	s_sub_u32 s23, s17, s36
	s_lshr_b32 s33, s22, 1
	s_and_b32 s35, s22, 1
	s_lshl_b32 s23, s23, 4
	v_add_u32_e32 v148, s23, v2
	global_load_dwordx4 v[16:19], v148, s[26:27]
	global_load_dwordx4 v[20:23], v148, s[24:25]
	global_load_dwordx4 v[24:27], v148, s[8:9]
	global_load_dwordx4 v[28:31], v148, s[0:1]
	s_lshl_b32 s36, s33, 2
	s_add_u32 s37, s36, 2
	s_add_u32 s37, s37, s35
	s_cmp_eq_u32 s35, 0
	s_cselect_b32 s38, -3, 2
	s_cselect_b32 s39, -4, -3
	s_add_i32 s38, s36, s38
	s_add_i32 s39, s36, s39
	s_max_i32 s38, s38, 0
	s_max_i32 s39, s39, 0
	s_mul_i32 s37, s37, 0x5800
	s_add_u32 s37, s37, s23
	s_add_u32 s37, s37, 0x1ec00000
	v_add_u32_e32 v149, s37, v2
	global_load_dwordx4 v[40:43], v149, s[52:53]
	s_mul_i32 s38, s38, 0x5800
	s_add_u32 s38, s38, s23
	s_add_u32 s38, s38, 0x1ec00000
	v_add_u32_e32 v149, s38, v2
	global_load_dwordx4 v[36:39], v149, s[52:53]
	s_mul_i32 s39, s39, 0x5800
	s_add_u32 s39, s39, s23
	s_add_u32 s39, s39, 0x1ec00000
	v_add_u32_e32 v149, s39, v2
	global_load_dwordx4 v[32:35], v149, s[52:53]
	s_lshl_b32 s37, s33, 1
	s_add_u32 s37, s37, s35
	s_mul_i32 s37, s37, 0x5800
	s_add_u32 s37, s37, s23
	s_add_u32 s37, s37, 0x21800000
	v_add_u32_e32 v149, s37, v2
	global_load_dwordx4 v[44:47], v149, s[52:53]
	s_lshl_b32 s37, s33, 6
	s_add_u32 s37, s37, s35
	s_mul_i32 s37, s37, 0x2c00
	s_lshr_b32 s38, s23, 1
	s_add_u32 s37, s37, s38
	s_add_u32 s37, s37, 0x8c00000
	v_add_u32_e32 v144, s37, v3
	s_and_b32 s36, s33, 255
	s_cmp_eq_u32 s36, 0
	s_cselect_b32 s36, 1, 0
	s_xor_b32 s37, s35, 1
	s_and_b32 s37, s37, s36
	v_writelane_b32 v4, s36, 0
	v_writelane_b32 v4, s37, 1
	s_mul_i32 s36, s16, 1
	s_add_u32 s17, s2, s36
	s_cmp_lt_u32 s17, 1441792
	s_cselect_b32 s17, s17, s28
	s_lshr_b32 s36, s17, 7
	s_mul_hi_u32 s22, s36, 0xba2e8ba3
	s_lshr_b32 s22, s22, 3
	s_mul_i32 s36, s22, 1408
	s_sub_u32 s23, s17, s36
	s_lshr_b32 s33, s22, 1
	s_and_b32 s35, s22, 1
	s_lshl_b32 s23, s23, 4
	v_add_u32_e32 v148, s23, v2
	global_load_dwordx4 v[48:51], v148, s[26:27]
	global_load_dwordx4 v[52:55], v148, s[24:25]
	global_load_dwordx4 v[56:59], v148, s[8:9]
	global_load_dwordx4 v[60:63], v148, s[0:1]
	s_lshl_b32 s36, s33, 2
	s_add_u32 s37, s36, 2
	s_add_u32 s37, s37, s35
	s_cmp_eq_u32 s35, 0
	s_cselect_b32 s38, -3, 2
	s_cselect_b32 s39, -4, -3
	s_add_i32 s38, s36, s38
	s_add_i32 s39, s36, s39
	s_max_i32 s38, s38, 0
	s_max_i32 s39, s39, 0
	s_mul_i32 s37, s37, 0x5800
	s_add_u32 s37, s37, s23
	s_add_u32 s37, s37, 0x1ec00000
	v_add_u32_e32 v149, s37, v2
	global_load_dwordx4 v[72:75], v149, s[52:53]
	s_mul_i32 s38, s38, 0x5800
	s_add_u32 s38, s38, s23
	s_add_u32 s38, s38, 0x1ec00000
	v_add_u32_e32 v149, s38, v2
	global_load_dwordx4 v[68:71], v149, s[52:53]
	s_mul_i32 s39, s39, 0x5800
	s_add_u32 s39, s39, s23
	s_add_u32 s39, s39, 0x1ec00000
	v_add_u32_e32 v149, s39, v2
	global_load_dwordx4 v[64:67], v149, s[52:53]
	s_lshl_b32 s37, s33, 1
	s_add_u32 s37, s37, s35
	s_mul_i32 s37, s37, 0x5800
	s_add_u32 s37, s37, s23
	s_add_u32 s37, s37, 0x21800000
	v_add_u32_e32 v149, s37, v2
	global_load_dwordx4 v[76:79], v149, s[52:53]
	s_lshl_b32 s37, s33, 6
	s_add_u32 s37, s37, s35
	s_mul_i32 s37, s37, 0x2c00
	s_lshr_b32 s38, s23, 1
	s_add_u32 s37, s37, s38
	s_add_u32 s37, s37, 0x8c00000
	v_add_u32_e32 v145, s37, v3
	s_and_b32 s36, s33, 255
	s_cmp_eq_u32 s36, 0
	s_cselect_b32 s36, 1, 0
	s_xor_b32 s37, s35, 1
	s_and_b32 s37, s37, s36
	v_writelane_b32 v4, s36, 2
	v_writelane_b32 v4, s37, 3
	s_mul_i32 s36, s16, 2
	s_add_u32 s17, s2, s36
	s_cmp_lt_u32 s17, 1441792
	s_cselect_b32 s17, s17, s28
	s_lshr_b32 s36, s17, 7
	s_mul_hi_u32 s22, s36, 0xba2e8ba3
	s_lshr_b32 s22, s22, 3
	s_mul_i32 s36, s22, 1408
	s_sub_u32 s23, s17, s36
	s_lshr_b32 s33, s22, 1
	s_and_b32 s35, s22, 1
	s_lshl_b32 s23, s23, 4
	v_add_u32_e32 v148, s23, v2
	global_load_dwordx4 v[80:83], v148, s[26:27]
	global_load_dwordx4 v[84:87], v148, s[24:25]
	global_load_dwordx4 v[88:91], v148, s[8:9]
	global_load_dwordx4 v[92:95], v148, s[0:1]
	s_lshl_b32 s36, s33, 2
	s_add_u32 s37, s36, 2
	s_add_u32 s37, s37, s35
	s_cmp_eq_u32 s35, 0
	s_cselect_b32 s38, -3, 2
	s_cselect_b32 s39, -4, -3
	s_add_i32 s38, s36, s38
	s_add_i32 s39, s36, s39
	s_max_i32 s38, s38, 0
	s_max_i32 s39, s39, 0
	s_mul_i32 s37, s37, 0x5800
	s_add_u32 s37, s37, s23
	s_add_u32 s37, s37, 0x1ec00000
	v_add_u32_e32 v149, s37, v2
	global_load_dwordx4 v[104:107], v149, s[52:53]
	s_mul_i32 s38, s38, 0x5800
	s_add_u32 s38, s38, s23
	s_add_u32 s38, s38, 0x1ec00000
	v_add_u32_e32 v149, s38, v2
	global_load_dwordx4 v[100:103], v149, s[52:53]
	s_mul_i32 s39, s39, 0x5800
	s_add_u32 s39, s39, s23
	s_add_u32 s39, s39, 0x1ec00000
	v_add_u32_e32 v149, s39, v2
	global_load_dwordx4 v[96:99], v149, s[52:53]
	s_lshl_b32 s37, s33, 1
	s_add_u32 s37, s37, s35
	s_mul_i32 s37, s37, 0x5800
	s_add_u32 s37, s37, s23
	s_add_u32 s37, s37, 0x21800000
	v_add_u32_e32 v149, s37, v2
	global_load_dwordx4 v[108:111], v149, s[52:53]
; __global__ void __launch_bounds__(512) fwd_mega(Args a) {
;     ...
;         for (int i = bx * 512 + tid; i < 1024 * NF4; i += G * 512) { const int f = (i % NF4) * 4, rj = i / NF4, jb = rj >> 1, ii = rj & 1; const bool first = (jb & 255) == 0;
;             const f32x4 z = {0.f, 0.f, 0.f, 0.f};
;             const f32x4 a0 = *(const f32x4*)(AH + ((size_t)jb * 4 + 2 + ii) * DFF + f);
;             const f32x4 pm1 = first ? z : *(const f32x4*)(AH + ((size_t)(jb - 1) * 4 + 1) * DFF + f);
;             const f32x4 pm2 = first ? z : *(const f32x4*)(AH + ((size_t)(jb - 1) * 4 + 0) * DFF + f);
;             const f32x4 a1 = ii ? *(const f32x4*)(AH + ((size_t)jb * 4 + 2) * DFF + f) : pm1;
;             const f32x4 a2 = ii ? pm1 : pm2;
;             const f32x4 bv = *(const f32x4*)(BH + ((size_t)jb * 2 + ii) * DFF + f);
;             const f32x4 c = *(const f32x4*)(a.conv_b + f) + *(const f32x4*)(a.conv_w + f) * a2 + *(const f32x4*)(a.conv_w + DFF + f) * a1 + *(const f32x4*)(a.conv_w + 2 * DFF + f) * a0;
;             float o[4];
; #pragma unroll
;             for (int e = 0; e < 4; ++e) { const float x = c[e]; const float uu = 0.7978845608028654f * (x + 0.044715f * x * x * x);
;                 o[e] = x * __builtin_amdgcn_rcpf(1.f + __builtin_amdgcn_exp2f(-2.885390081777927f * uu)) * bv[e]; }
	s_lshl_b32 s37, s33, 6
	s_add_u32 s37, s37, s35
	s_mul_i32 s37, s37, 0x2c00
	s_lshr_b32 s38, s23, 1
	s_add_u32 s37, s37, s38
	s_add_u32 s37, s37, 0x8c00000
	v_add_u32_e32 v146, s37, v3
	s_and_b32 s36, s33, 255
	s_cmp_eq_u32 s36, 0
	s_cselect_b32 s36, 1, 0
	s_xor_b32 s37, s35, 1
	s_and_b32 s37, s37, s36
	v_writelane_b32 v4, s36, 4
	v_writelane_b32 v4, s37, 5
	s_mul_i32 s36, s16, 3
	s_add_u32 s17, s2, s36
	s_cmp_lt_u32 s17, 1441792
	s_cselect_b32 s17, s17, s28
	s_lshr_b32 s36, s17, 7
	s_mul_hi_u32 s22, s36, 0xba2e8ba3
	s_lshr_b32 s22, s22, 3
	s_mul_i32 s36, s22, 1408
	s_sub_u32 s23, s17, s36
	s_lshr_b32 s33, s22, 1
	s_and_b32 s35, s22, 1
	s_lshl_b32 s23, s23, 4
	v_add_u32_e32 v148, s23, v2
	global_load_dwordx4 v[112:115], v148, s[26:27]
	global_load_dwordx4 v[116:119], v148, s[24:25]
	global_load_dwordx4 v[120:123], v148, s[8:9]
	global_load_dwordx4 v[124:127], v148, s[0:1]
	s_lshl_b32 s36, s33, 2
	s_add_u32 s37, s36, 2
	s_add_u32 s37, s37, s35
	s_cmp_eq_u32 s35, 0
	s_cselect_b32 s38, -3, 2
	s_cselect_b32 s39, -4, -3
	s_add_i32 s38, s36, s38
	s_add_i32 s39, s36, s39
	s_max_i32 s38, s38, 0
	s_max_i32 s39, s39, 0
	s_mul_i32 s37, s37, 0x5800
	s_add_u32 s37, s37, s23
	s_add_u32 s37, s37, 0x1ec00000
	v_add_u32_e32 v149, s37, v2
	global_load_dwordx4 v[136:139], v149, s[52:53]
	s_mul_i32 s38, s38, 0x5800
	s_add_u32 s38, s38, s23
	s_add_u32 s38, s38, 0x1ec00000
	v_add_u32_e32 v149, s38, v2
	global_load_dwordx4 v[132:135], v149, s[52:53]
	s_mul_i32 s39, s39, 0x5800
	s_add_u32 s39, s39, s23
	s_add_u32 s39, s39, 0x1ec00000
	v_add_u32_e32 v149, s39, v2
	global_load_dwordx4 v[128:131], v149, s[52:53]
	s_lshl_b32 s37, s33, 1
	s_add_u32 s37, s37, s35
	s_mul_i32 s37, s37, 0x5800
	s_add_u32 s37, s37, s23
	s_add_u32 s37, s37, 0x21800000
	v_add_u32_e32 v149, s37, v2
	global_load_dwordx4 v[140:143], v149, s[52:53]
	s_lshl_b32 s37, s33, 6
	s_add_u32 s37, s37, s35
	s_mul_i32 s37, s37, 0x2c00
	s_lshr_b32 s38, s23, 1
	s_add_u32 s37, s37, s38
	s_add_u32 s37, s37, 0x8c00000
	v_add_u32_e32 v147, s37, v3
	s_and_b32 s36, s33, 255
	s_cmp_eq_u32 s36, 0
	s_cselect_b32 s36, 1, 0
	s_xor_b32 s37, s35, 1
	s_and_b32 s37, s37, s36
	v_writelane_b32 v4, s36, 6
	v_writelane_b32 v4, s37, 7
	s_waitcnt vmcnt(0)
	v_readlane_b32 s36, v4, 0
	v_readlane_b32 s37, v4, 1
	s_nop 3
	s_cmp_eq_u32 s36, 0
	s_cbranch_scc1 .Lp9_z0a
	v_mov_b32_e32 v32, 0
	v_mov_b32_e32 v33, 0
	v_mov_b32_e32 v34, 0
	v_mov_b32_e32 v35, 0
.Lp9_z0a:
	s_cmp_eq_u32 s37, 0
	s_cbranch_scc1 .Lp9_z0b
	v_mov_b32_e32 v36, 0
	v_mov_b32_e32 v37, 0
	v_mov_b32_e32 v38, 0
	v_mov_b32_e32 v39, 0
.Lp9_z0b:
	v_pk_fma_f32 v[16:17], v[20:21], v[32:33], v[16:17]
	v_pk_fma_f32 v[18:19], v[22:23], v[34:35], v[18:19]
	v_pk_fma_f32 v[16:17], v[24:25], v[36:37], v[16:17]
	v_pk_fma_f32 v[18:19], v[26:27], v[38:39], v[18:19]
	v_pk_fma_f32 v[16:17], v[28:29], v[40:41], v[16:17]
	v_pk_fma_f32 v[18:19], v[30:31], v[42:43], v[18:19]
	v_mul_f32_e32 v20, 0x3d372713, v16
	v_mul_f32_e32 v21, 0x3d372713, v17
	v_mul_f32_e32 v22, 0x3d372713, v18
	v_mul_f32_e32 v23, 0x3d372713, v19
	v_mul_f32_e32 v20, v16, v20
	v_mul_f32_e32 v21, v17, v21
	v_mul_f32_e32 v22, v18, v22
	v_mul_f32_e32 v23, v19, v23
	v_fma_f32 v20, v16, v20, v16
	v_fma_f32 v21, v17, v21, v17
	v_fma_f32 v22, v18, v22, v18
	v_fma_f32 v23, v19, v23, v19
	v_mul_f32_e32 v20, 0x3f4c422a, v20
	v_mul_f32_e32 v21, 0x3f4c422a, v21
	v_mul_f32_e32 v22, 0x3f4c422a, v22
	v_mul_f32_e32 v23, 0x3f4c422a, v23
	v_mul_f32_e32 v20, 0xc038aa3b, v20
	v_mul_f32_e32 v21, 0xc038aa3b, v21
	v_mul_f32_e32 v22, 0xc038aa3b, v22
	v_mul_f32_e32 v23, 0xc038aa3b, v23
	v_exp_f32_e32 v20, v20
	v_exp_f32_e32 v21, v21
	v_exp_f32_e32 v22, v22
	v_exp_f32_e32 v23, v23
	s_nop 0
	v_add_f32_e32 v20, 1.0, v20
	v_add_f32_e32 v21, 1.0, v21
	v_add_f32_e32 v22, 1.0, v22
	v_add_f32_e32 v23, 1.0, v23
	v_rcp_f32_e32 v20, v20
	v_rcp_f32_e32 v21, v21
	v_rcp_f32_e32 v22, v22
	v_rcp_f32_e32 v23, v23
	s_nop 0
	v_pk_mul_f32 v[16:17], v[16:17], v[20:21]
	v_pk_mul_f32 v[18:19], v[18:19], v[22:23]
	v_pk_mul_f32 v[16:17], v[44:45], v[16:17]
	v_pk_mul_f32 v[18:19], v[46:47], v[18:19]
	v_cvt_pk_bf16_f32 v16, v16, v17
	v_cvt_pk_bf16_f32 v17, v18, v19
	global_store_dwordx2 v144, v[16:17], s[52:53]
	v_readlane_b32 s36, v4, 2
	v_readlane_b32 s37, v4, 3
	s_nop 3
	s_cmp_eq_u32 s36, 0
	s_cbranch_scc1 .Lp9_z1a
	v_mov_b32_e32 v64, 0
	v_mov_b32_e32 v65, 0
	v_mov_b32_e32 v66, 0
	v_mov_b32_e32 v67, 0
.Lp9_z1a:
	s_cmp_eq_u32 s37, 0
	s_cbranch_scc1 .Lp9_z1b
	v_mov_b32_e32 v68, 0
	v_mov_b32_e32 v69, 0
	v_mov_b32_e32 v70, 0
	v_mov_b32_e32 v71, 0
; __device__ __forceinline__ unsigned pk2(float lo, float hi) { return f2bf(lo) | (f2bf(hi) << 16); }
; __global__ void __launch_bounds__(512) fwd_mega(Args a) {
;     ...
;         for (int i = bx * 512 + tid; i < 1024 * NF4; i += G * 512) { const int f = (i % NF4) * 4, rj = i / NF4, jb = rj >> 1, ii = rj & 1; const bool first = (jb & 255) == 0;
;             const f32x4 z = {0.f, 0.f, 0.f, 0.f};
;             const f32x4 a0 = *(const f32x4*)(AH + ((size_t)jb * 4 + 2 + ii) * DFF + f);
;             const f32x4 pm1 = first ? z : *(const f32x4*)(AH + ((size_t)(jb - 1) * 4 + 1) * DFF + f);
;             const f32x4 pm2 = first ? z : *(const f32x4*)(AH + ((size_t)(jb - 1) * 4 + 0) * DFF + f);
;             const f32x4 a1 = ii ? *(const f32x4*)(AH + ((size_t)jb * 4 + 2) * DFF + f) : pm1;
;             const f32x4 a2 = ii ? pm1 : pm2;
;             const f32x4 bv = *(const f32x4*)(BH + ((size_t)jb * 2 + ii) * DFF + f);
;             const f32x4 c = *(const f32x4*)(a.conv_b + f) + *(const f32x4*)(a.conv_w + f) * a2 + *(const f32x4*)(a.conv_w + DFF + f) * a1 + *(const f32x4*)(a.conv_w + 2 * DFF + f) * a0;
;             float o[4];
; #pragma unroll
;             for (int e = 0; e < 4; ++e) { const float x = c[e]; const float uu = 0.7978845608028654f * (x + 0.044715f * x * x * x);
;                 o[e] = x * __builtin_amdgcn_rcpf(1.f + __builtin_amdgcn_exp2f(-2.885390081777927f * uu)) * bv[e]; }
;             *(unsigned long long*)(GG + ((size_t)jb * 64 + ii) * DFF + f) = (unsigned long long)pk2(o[0], o[1]) | ((unsigned long long)pk2(o[2], o[3]) << 32); }
.Lp9_z1b:
	v_pk_fma_f32 v[48:49], v[52:53], v[64:65], v[48:49]
	v_pk_fma_f32 v[50:51], v[54:55], v[66:67], v[50:51]
	v_pk_fma_f32 v[48:49], v[56:57], v[68:69], v[48:49]
	v_pk_fma_f32 v[50:51], v[58:59], v[70:71], v[50:51]
	v_pk_fma_f32 v[48:49], v[60:61], v[72:73], v[48:49]
	v_pk_fma_f32 v[50:51], v[62:63], v[74:75], v[50:51]
	v_mul_f32_e32 v52, 0x3d372713, v48
	v_mul_f32_e32 v53, 0x3d372713, v49
	v_mul_f32_e32 v54, 0x3d372713, v50
	v_mul_f32_e32 v55, 0x3d372713, v51
	v_mul_f32_e32 v52, v48, v52
	v_mul_f32_e32 v53, v49, v53
	v_mul_f32_e32 v54, v50, v54
	v_mul_f32_e32 v55, v51, v55
	v_fma_f32 v52, v48, v52, v48
	v_fma_f32 v53, v49, v53, v49
	v_fma_f32 v54, v50, v54, v50
	v_fma_f32 v55, v51, v55, v51
	v_mul_f32_e32 v52, 0x3f4c422a, v52
	v_mul_f32_e32 v53, 0x3f4c422a, v53
	v_mul_f32_e32 v54, 0x3f4c422a, v54
	v_mul_f32_e32 v55, 0x3f4c422a, v55
	v_mul_f32_e32 v52, 0xc038aa3b, v52
	v_mul_f32_e32 v53, 0xc038aa3b, v53
	v_mul_f32_e32 v54, 0xc038aa3b, v54
	v_mul_f32_e32 v55, 0xc038aa3b, v55
	v_exp_f32_e32 v52, v52
	v_exp_f32_e32 v53, v53
	v_exp_f32_e32 v54, v54
	v_exp_f32_e32 v55, v55
	s_nop 0
	v_add_f32_e32 v52, 1.0, v52
	v_add_f32_e32 v53, 1.0, v53
	v_add_f32_e32 v54, 1.0, v54
	v_add_f32_e32 v55, 1.0, v55
	v_rcp_f32_e32 v52, v52
	v_rcp_f32_e32 v53, v53
	v_rcp_f32_e32 v54, v54
	v_rcp_f32_e32 v55, v55
	s_nop 0
	v_pk_mul_f32 v[48:49], v[48:49], v[52:53]
	v_pk_mul_f32 v[50:51], v[50:51], v[54:55]
	v_pk_mul_f32 v[48:49], v[76:77], v[48:49]
	v_pk_mul_f32 v[50:51], v[78:79], v[50:51]
	v_cvt_pk_bf16_f32 v48, v48, v49
	v_cvt_pk_bf16_f32 v49, v50, v51
	global_store_dwordx2 v145, v[48:49], s[52:53]
	v_readlane_b32 s36, v4, 4
	v_readlane_b32 s37, v4, 5
	s_nop 3
	s_cmp_eq_u32 s36, 0
	s_cbranch_scc1 .Lp9_z2a
	v_mov_b32_e32 v96, 0
	v_mov_b32_e32 v97, 0
	v_mov_b32_e32 v98, 0
	v_mov_b32_e32 v99, 0
.Lp9_z2a:
	s_cmp_eq_u32 s37, 0
	s_cbranch_scc1 .Lp9_z2b
	v_mov_b32_e32 v100, 0
	v_mov_b32_e32 v101, 0
	v_mov_b32_e32 v102, 0
	v_mov_b32_e32 v103, 0
.Lp9_z2b:
	v_pk_fma_f32 v[80:81], v[84:85], v[96:97], v[80:81]
	v_pk_fma_f32 v[82:83], v[86:87], v[98:99], v[82:83]
	v_pk_fma_f32 v[80:81], v[88:89], v[100:101], v[80:81]
	v_pk_fma_f32 v[82:83], v[90:91], v[102:103], v[82:83]
	v_pk_fma_f32 v[80:81], v[92:93], v[104:105], v[80:81]
	v_pk_fma_f32 v[82:83], v[94:95], v[106:107], v[82:83]
	v_mul_f32_e32 v84, 0x3d372713, v80
	v_mul_f32_e32 v85, 0x3d372713, v81
	v_mul_f32_e32 v86, 0x3d372713, v82
	v_mul_f32_e32 v87, 0x3d372713, v83
	v_mul_f32_e32 v84, v80, v84
	v_mul_f32_e32 v85, v81, v85
	v_mul_f32_e32 v86, v82, v86
	v_mul_f32_e32 v87, v83, v87
	v_fma_f32 v84, v80, v84, v80
	v_fma_f32 v85, v81, v85, v81
	v_fma_f32 v86, v82, v86, v82
	v_fma_f32 v87, v83, v87, v83
	v_mul_f32_e32 v84, 0x3f4c422a, v84
	v_mul_f32_e32 v85, 0x3f4c422a, v85
	v_mul_f32_e32 v86, 0x3f4c422a, v86
	v_mul_f32_e32 v87, 0x3f4c422a, v87
	v_mul_f32_e32 v84, 0xc038aa3b, v84
	v_mul_f32_e32 v85, 0xc038aa3b, v85
	v_mul_f32_e32 v86, 0xc038aa3b, v86
	v_mul_f32_e32 v87, 0xc038aa3b, v87
	v_exp_f32_e32 v84, v84
	v_exp_f32_e32 v85, v85
	v_exp_f32_e32 v86, v86
	v_exp_f32_e32 v87, v87
	s_nop 0
	v_add_f32_e32 v84, 1.0, v84
	v_add_f32_e32 v85, 1.0, v85
	v_add_f32_e32 v86, 1.0, v86
	v_add_f32_e32 v87, 1.0, v87
	v_rcp_f32_e32 v84, v84
	v_rcp_f32_e32 v85, v85
	v_rcp_f32_e32 v86, v86
	v_rcp_f32_e32 v87, v87
	s_nop 0
	v_pk_mul_f32 v[80:81], v[80:81], v[84:85]
	v_pk_mul_f32 v[82:83], v[82:83], v[86:87]
	v_pk_mul_f32 v[80:81], v[108:109], v[80:81]
	v_pk_mul_f32 v[82:83], v[110:111], v[82:83]
	v_cvt_pk_bf16_f32 v80, v80, v81
	v_cvt_pk_bf16_f32 v81, v82, v83
	global_store_dwordx2 v146, v[80:81], s[52:53]
	v_readlane_b32 s36, v4, 6
	v_readlane_b32 s37, v4, 7
	s_nop 3
	s_cmp_eq_u32 s36, 0
	s_cbranch_scc1 .Lp9_z3a
	v_mov_b32_e32 v128, 0
	v_mov_b32_e32 v129, 0
	v_mov_b32_e32 v130, 0
	v_mov_b32_e32 v131, 0
.Lp9_z3a:
	s_cmp_eq_u32 s37, 0
	s_cbranch_scc1 .Lp9_z3b
	v_mov_b32_e32 v132, 0
	v_mov_b32_e32 v133, 0
	v_mov_b32_e32 v134, 0
	v_mov_b32_e32 v135, 0
.Lp9_z3b:
	v_pk_fma_f32 v[112:113], v[116:117], v[128:129], v[112:113]
	v_pk_fma_f32 v[114:115], v[118:119], v[130:131], v[114:115]
	v_pk_fma_f32 v[112:113], v[120:121], v[132:133], v[112:113]
	v_pk_fma_f32 v[114:115], v[122:123], v[134:135], v[114:115]
	v_pk_fma_f32 v[112:113], v[124:125], v[136:137], v[112:113]
	v_pk_fma_f32 v[114:115], v[126:127], v[138:139], v[114:115]
	v_mul_f32_e32 v116, 0x3d372713, v112
	v_mul_f32_e32 v117, 0x3d372713, v113
	v_mul_f32_e32 v118, 0x3d372713, v114
	v_mul_f32_e32 v119, 0x3d372713, v115
	v_mul_f32_e32 v116, v112, v116
	v_mul_f32_e32 v117, v113, v117
	v_mul_f32_e32 v118, v114, v118
	v_mul_f32_e32 v119, v115, v119
	v_fma_f32 v116, v112, v116, v112
	v_fma_f32 v117, v113, v117, v113
	v_fma_f32 v118, v114, v118, v114
	v_fma_f32 v119, v115, v119, v115
	v_mul_f32_e32 v116, 0x3f4c422a, v116
	v_mul_f32_e32 v117, 0x3f4c422a, v117
	v_mul_f32_e32 v118, 0x3f4c422a, v118
	v_mul_f32_e32 v119, 0x3f4c422a, v119
	v_mul_f32_e32 v116, 0xc038aa3b, v116
	v_mul_f32_e32 v117, 0xc038aa3b, v117
	v_mul_f32_e32 v118, 0xc038aa3b, v118
	v_mul_f32_e32 v119, 0xc038aa3b, v119
	v_exp_f32_e32 v116, v116
	v_exp_f32_e32 v117, v117
	v_exp_f32_e32 v118, v118
	v_exp_f32_e32 v119, v119
	s_nop 0
	v_add_f32_e32 v116, 1.0, v116
	v_add_f32_e32 v117, 1.0, v117
	v_add_f32_e32 v118, 1.0, v118
	v_add_f32_e32 v119, 1.0, v119
	v_rcp_f32_e32 v116, v116
	v_rcp_f32_e32 v117, v117
	v_rcp_f32_e32 v118, v118
	v_rcp_f32_e32 v119, v119
	s_nop 0
	v_pk_mul_f32 v[112:113], v[112:113], v[116:117]
	v_pk_mul_f32 v[114:115], v[114:115], v[118:119]
	v_pk_mul_f32 v[112:113], v[140:141], v[112:113]
	v_pk_mul_f32 v[114:115], v[142:143], v[114:115]
	v_cvt_pk_bf16_f32 v112, v112, v113
	v_cvt_pk_bf16_f32 v113, v114, v115
	global_store_dwordx2 v147, v[112:113], s[52:53]
	s_lshl_b32 s36, s16, 2
	s_add_u32 s2, s2, s36
	s_cmp_lt_u32 s2, 1441792
	s_cbranch_scc1 .Lp9_batch
.Lp9_done:
.LBB0_953:
	s_or_b64 exec, exec, s[6:7]
